# phase0 adaLN GEMV item: 32 weight loads in flight per trip (4 trips) instead of 16 trips of 8 loads each with a full wait
# speedup vs baseline: 1.0033x; 1.0033x over previous
.LBB0_76:
	s_mul_hi_i32 s6, s30, 0x2aaaaaab
	s_load_dwordx2 s[10:11], s[0:1], 0x20
	s_lshr_b32 s7, s6, 31
	s_ashr_i32 s6, s6, 4
	s_add_i32 s8, s6, s7
	s_ashr_i32 s9, s8, 31
	s_mul_i32 s6, s8, 0x60
	s_lshl_b64 s[12:13], s[8:9], 10
	s_sub_i32 s6, s30, s6
	v_lshl_add_u64 v[0:1], s[12:13], 0, v[16:17]
	s_waitcnt lgkmcnt(0)
	v_mov_b64_e32 v[2:3], s[10:11]
	s_lshl_b32 s6, s6, 6
	v_mad_u64_u32 v[2:3], s[10:11], v0, s59, v[2:3]
	v_mad_i32_i24 v3, v1, s59, v3
	s_ashr_i32 s7, s6, 31
	v_lshl_add_u64 v[0:1], s[6:7], 2, v[2:3]
	v_lshlrev_b32_e32 v18, 2, v12
	v_mov_b32_e32 v4, 0
	v_lshl_add_u64 v[0:1], v[0:1], 0, v[18:19]
	s_mov_b64 s[10:11], 0
	v_mov_b32_e32 v5, v9
	v_mov_b32_e32 v2, 0
	v_mov_b32_e32 v3, v4
	s_mov_b32 s66, 0x6000
	s_mov_b32 s67, 0
.LBB0_77:
	v_lshl_add_u64 v[6:7], v[0:1], 0, s[10:11]
	global_load_dword v191, v[6:7], off
	v_lshl_add_u64 v[6:7], v[6:7], 0, s[66:67]
	global_load_dword v192, v[6:7], off
	v_lshl_add_u64 v[6:7], v[6:7], 0, s[66:67]
	global_load_dword v193, v[6:7], off
	v_lshl_add_u64 v[6:7], v[6:7], 0, s[66:67]
	global_load_dword v194, v[6:7], off
	v_lshl_add_u64 v[6:7], v[6:7], 0, s[66:67]
	global_load_dword v195, v[6:7], off
	v_lshl_add_u64 v[6:7], v[6:7], 0, s[66:67]
	global_load_dword v196, v[6:7], off
	v_lshl_add_u64 v[6:7], v[6:7], 0, s[66:67]
	global_load_dword v197, v[6:7], off
	v_lshl_add_u64 v[6:7], v[6:7], 0, s[66:67]
	global_load_dword v198, v[6:7], off
	v_lshl_add_u64 v[6:7], v[6:7], 0, s[66:67]
	global_load_dword v199, v[6:7], off
	v_lshl_add_u64 v[6:7], v[6:7], 0, s[66:67]
	global_load_dword v200, v[6:7], off
	v_lshl_add_u64 v[6:7], v[6:7], 0, s[66:67]
	global_load_dword v201, v[6:7], off
	v_lshl_add_u64 v[6:7], v[6:7], 0, s[66:67]
	global_load_dword v202, v[6:7], off
	v_lshl_add_u64 v[6:7], v[6:7], 0, s[66:67]
	global_load_dword v203, v[6:7], off
	v_lshl_add_u64 v[6:7], v[6:7], 0, s[66:67]
	global_load_dword v204, v[6:7], off
	v_lshl_add_u64 v[6:7], v[6:7], 0, s[66:67]
	global_load_dword v205, v[6:7], off
	v_lshl_add_u64 v[6:7], v[6:7], 0, s[66:67]
	global_load_dword v206, v[6:7], off
	v_lshl_add_u64 v[6:7], v[6:7], 0, s[66:67]
	global_load_dword v207, v[6:7], off
	v_lshl_add_u64 v[6:7], v[6:7], 0, s[66:67]
	global_load_dword v208, v[6:7], off
	v_lshl_add_u64 v[6:7], v[6:7], 0, s[66:67]
	global_load_dword v209, v[6:7], off
	v_lshl_add_u64 v[6:7], v[6:7], 0, s[66:67]
	global_load_dword v210, v[6:7], off
	v_lshl_add_u64 v[6:7], v[6:7], 0, s[66:67]
	global_load_dword v211, v[6:7], off
	v_lshl_add_u64 v[6:7], v[6:7], 0, s[66:67]
	global_load_dword v212, v[6:7], off
	v_lshl_add_u64 v[6:7], v[6:7], 0, s[66:67]
	global_load_dword v213, v[6:7], off
	v_lshl_add_u64 v[6:7], v[6:7], 0, s[66:67]
	global_load_dword v214, v[6:7], off
	v_lshl_add_u64 v[6:7], v[6:7], 0, s[66:67]
	global_load_dword v215, v[6:7], off
	v_lshl_add_u64 v[6:7], v[6:7], 0, s[66:67]
	global_load_dword v216, v[6:7], off
	v_lshl_add_u64 v[6:7], v[6:7], 0, s[66:67]
	global_load_dword v217, v[6:7], off
	v_lshl_add_u64 v[6:7], v[6:7], 0, s[66:67]
	global_load_dword v218, v[6:7], off
	v_lshl_add_u64 v[6:7], v[6:7], 0, s[66:67]
	global_load_dword v219, v[6:7], off
	v_lshl_add_u64 v[6:7], v[6:7], 0, s[66:67]
	global_load_dword v220, v[6:7], off
	v_lshl_add_u64 v[6:7], v[6:7], 0, s[66:67]
	global_load_dword v221, v[6:7], off
	v_lshl_add_u64 v[6:7], v[6:7], 0, s[66:67]
	global_load_dword v222, v[6:7], off
	ds_read_b128 v[32:35], v5
	ds_read_b128 v[36:39], v5 offset:16
	ds_read_b128 v[40:43], v5 offset:4096
	ds_read_b128 v[44:47], v5 offset:4112
	ds_read_b128 v[48:51], v5 offset:8192
	ds_read_b128 v[52:55], v5 offset:8208
	v_add_u32_e32 v5, 32, v5
	s_waitcnt vmcnt(24) lgkmcnt(0)
	v_fmac_f32_e32 v2, v191, v32
	v_fmac_f32_e32 v3, v191, v40
	v_fmac_f32_e32 v4, v191, v48
	v_fmac_f32_e32 v2, v192, v33
	v_fmac_f32_e32 v3, v192, v41
	v_fmac_f32_e32 v4, v192, v49
	v_fmac_f32_e32 v2, v193, v34
	v_fmac_f32_e32 v3, v193, v42
	v_fmac_f32_e32 v4, v193, v50
	v_fmac_f32_e32 v2, v194, v35
	v_fmac_f32_e32 v3, v194, v43
	v_fmac_f32_e32 v4, v194, v51
	v_fmac_f32_e32 v2, v195, v36
	v_fmac_f32_e32 v3, v195, v44
	v_fmac_f32_e32 v4, v195, v52
	v_fmac_f32_e32 v2, v196, v37
	v_fmac_f32_e32 v3, v196, v45
	v_fmac_f32_e32 v4, v196, v53
	v_fmac_f32_e32 v2, v197, v38
	v_fmac_f32_e32 v3, v197, v46
	v_fmac_f32_e32 v4, v197, v54
	v_fmac_f32_e32 v2, v198, v39
	v_fmac_f32_e32 v3, v198, v47
	v_fmac_f32_e32 v4, v198, v55
	ds_read_b128 v[32:35], v5
	ds_read_b128 v[36:39], v5 offset:16
	ds_read_b128 v[40:43], v5 offset:4096
	ds_read_b128 v[44:47], v5 offset:4112
	ds_read_b128 v[48:51], v5 offset:8192
	ds_read_b128 v[52:55], v5 offset:8208
	v_add_u32_e32 v5, 32, v5
	s_waitcnt vmcnt(16) lgkmcnt(0)
	v_fmac_f32_e32 v2, v199, v32
	v_fmac_f32_e32 v3, v199, v40
	v_fmac_f32_e32 v4, v199, v48
	v_fmac_f32_e32 v2, v200, v33
	v_fmac_f32_e32 v3, v200, v41
	v_fmac_f32_e32 v4, v200, v49
	v_fmac_f32_e32 v2, v201, v34
	v_fmac_f32_e32 v3, v201, v42
	v_fmac_f32_e32 v4, v201, v50
	v_fmac_f32_e32 v2, v202, v35
	v_fmac_f32_e32 v3, v202, v43
	v_fmac_f32_e32 v4, v202, v51
	v_fmac_f32_e32 v2, v203, v36
	v_fmac_f32_e32 v3, v203, v44
	v_fmac_f32_e32 v4, v203, v52
	v_fmac_f32_e32 v2, v204, v37
	v_fmac_f32_e32 v3, v204, v45
	v_fmac_f32_e32 v4, v204, v53
	v_fmac_f32_e32 v2, v205, v38
	v_fmac_f32_e32 v3, v205, v46
	v_fmac_f32_e32 v4, v205, v54
	v_fmac_f32_e32 v2, v206, v39
	v_fmac_f32_e32 v3, v206, v47
	v_fmac_f32_e32 v4, v206, v55
	ds_read_b128 v[32:35], v5
	ds_read_b128 v[36:39], v5 offset:16
	ds_read_b128 v[40:43], v5 offset:4096
	ds_read_b128 v[44:47], v5 offset:4112
	ds_read_b128 v[48:51], v5 offset:8192
	ds_read_b128 v[52:55], v5 offset:8208
	v_add_u32_e32 v5, 32, v5
	s_waitcnt vmcnt(8) lgkmcnt(0)
	v_fmac_f32_e32 v2, v207, v32
	v_fmac_f32_e32 v3, v207, v40
	v_fmac_f32_e32 v4, v207, v48
	v_fmac_f32_e32 v2, v208, v33
	v_fmac_f32_e32 v3, v208, v41
	v_fmac_f32_e32 v4, v208, v49
	v_fmac_f32_e32 v2, v209, v34
	v_fmac_f32_e32 v3, v209, v42
	v_fmac_f32_e32 v4, v209, v50
	v_fmac_f32_e32 v2, v210, v35
	v_fmac_f32_e32 v3, v210, v43
	v_fmac_f32_e32 v4, v210, v51
	v_fmac_f32_e32 v2, v211, v36
	v_fmac_f32_e32 v3, v211, v44
	v_fmac_f32_e32 v4, v211, v52
	v_fmac_f32_e32 v2, v212, v37
	v_fmac_f32_e32 v3, v212, v45
	v_fmac_f32_e32 v4, v212, v53
	v_fmac_f32_e32 v2, v213, v38
	v_fmac_f32_e32 v3, v213, v46
	v_fmac_f32_e32 v4, v213, v54
	v_fmac_f32_e32 v2, v214, v39
	v_fmac_f32_e32 v3, v214, v47
	v_fmac_f32_e32 v4, v214, v55
	ds_read_b128 v[32:35], v5
	ds_read_b128 v[36:39], v5 offset:16
	ds_read_b128 v[40:43], v5 offset:4096
	ds_read_b128 v[44:47], v5 offset:4112
	ds_read_b128 v[48:51], v5 offset:8192
	ds_read_b128 v[52:55], v5 offset:8208
	v_add_u32_e32 v5, 32, v5
	s_waitcnt vmcnt(0) lgkmcnt(0)
	v_fmac_f32_e32 v2, v215, v32
	v_fmac_f32_e32 v3, v215, v40
	v_fmac_f32_e32 v4, v215, v48
	v_fmac_f32_e32 v2, v216, v33
	v_fmac_f32_e32 v3, v216, v41
	v_fmac_f32_e32 v4, v216, v49
	v_fmac_f32_e32 v2, v217, v34
	v_fmac_f32_e32 v3, v217, v42
	v_fmac_f32_e32 v4, v217, v50
	v_fmac_f32_e32 v2, v218, v35
	v_fmac_f32_e32 v3, v218, v43
	v_fmac_f32_e32 v4, v218, v51
	v_fmac_f32_e32 v2, v219, v36
	v_fmac_f32_e32 v3, v219, v44
	v_fmac_f32_e32 v4, v219, v52
	v_fmac_f32_e32 v2, v220, v37
	v_fmac_f32_e32 v3, v220, v45
	v_fmac_f32_e32 v4, v220, v53
	v_fmac_f32_e32 v2, v221, v38
	v_fmac_f32_e32 v3, v221, v46
	v_fmac_f32_e32 v4, v221, v54
	v_fmac_f32_e32 v2, v222, v39
	v_fmac_f32_e32 v3, v222, v47
	v_fmac_f32_e32 v4, v222, v55
	s_add_u32 s10, s10, 0xc0000
	s_addc_u32 s11, s11, 0
	s_cmp_eq_u32 s10, 0x300000
	s_cbranch_scc0 .LBB0_77
	ds_write2st64_b32 v20, v2, v3 offset0:48 offset1:49
	ds_write_b32 v20, v4 offset:12800
	s_waitcnt lgkmcnt(0)
	s_barrier
	s_and_saveexec_b64 s[10:11], s[4:5]
	s_cbranch_execz .LBB0_24
	s_load_dwordx2 s[12:13], s[0:1], 0x28
	s_load_dwordx2 s[20:21], s[0:1], 0xf0
	s_mul_i32 s9, s8, 0x1800
	s_add_i32 s9, s9, s6
	v_or_b32_e32 v0, s9, v12
	v_ashrrev_i32_e32 v1, 31, v0
	s_waitcnt lgkmcnt(0)
	v_lshl_add_u64 v[0:1], v[0:1], 2, s[12:13]
	global_load_dword v34, v[0:1], off
	ds_read2st64_b32 v[0:1], v21 offset0:48 offset1:51
	ds_read2st64_b32 v[2:3], v21 offset0:54 offset1:57
	ds_read2st64_b32 v[4:5], v21 offset0:60 offset1:63
	ds_read2st64_b32 v[6:7], v21 offset0:66 offset1:69
	v_mad_u64_u32 v[22:23], s[8:9], s8, 3, v[14:15]
	s_waitcnt lgkmcnt(3)
	v_add_f32_e32 v0, 0, v0
	v_add_f32_e32 v23, v0, v1
	s_waitcnt lgkmcnt(2)
	v_add_f32_e32 v2, v23, v2
	v_mov_b64_e32 v[32:33], s[20:21]
	v_add_f32_e32 v2, v2, v3
	v_mad_i64_i32 v[0:1], s[8:9], v22, s59, v[32:33]
	s_waitcnt lgkmcnt(1)
	v_add_f32_e32 v2, v2, v4
	v_lshl_add_u64 v[0:1], s[6:7], 2, v[0:1]
	v_add_f32_e32 v2, v2, v5
	v_lshl_add_u64 v[0:1], v[0:1], 0, v[18:19]
	s_waitcnt lgkmcnt(0)
	v_add_f32_e32 v2, v2, v6
	v_add_co_u32_e32 v0, vcc, 0x3180000, v0
	v_add_f32_e32 v2, v2, v7
	s_nop 0
	v_addc_co_u32_e32 v1, vcc, 0, v1, vcc
	s_waitcnt vmcnt(0)
	v_add_f32_e32 v2, v2, v34
	global_store_dword v[0:1], v2, off
	s_branch .LBB0_24
